# weight-converting workgroups write their L2 back themselves when done; XCD leader skips the write-back after the in-proj phase too
# baseline (speedup 1.0000x reference)
.Lcv_flush2:
	s_waitcnt vmcnt(0)
	s_barrier
	v_readfirstlane_b32 s98, v0
	s_cmp_gt_u32 s98, 63
	s_cbranch_scc1 .Lcv_noflushb
	buffer_wbl2 sc1
.Lcv_noflushb:
	s_branch .LBB0_995
.LBB0_826:
	s_or_b64 exec, exec, s[8:9]
	s_cbranch_execz .LBB0_648
	s_branch .LBB0_995

.Lxb_leader:
	v_readlane_b32 s98, v252, 2
	s_nop 0
	s_sub_i32 s98, s98, 4
	s_cmp_lt_i32 s98, 0
	s_cbranch_scc1 .Lxb_flush
	s_mul_i32 s99, s98, 0x1746
	s_lshr_b32 s99, s99, 16
	s_mul_i32 s99, s99, 11
	s_sub_i32 s98, s98, s99
	s_lshl_b32 s98, 1, s98
	s_and_b32 s98, s98, 0x6e1
	s_cmp_lg_u32 s98, 0
	s_cbranch_scc1 .Lxb_noflush
